# seams 4 and 5 (ret_out->w_o, w_o->up) also as 4-workgroup panel barriers with late global guards; decode rows handed over write-through
# speedup vs baseline: 1.0315x; 1.0183x over previous
.LBB0_722:
	v_readlane_b32 s36, v252, 0
	s_and_b32 s27, s15, 0x1c000
	v_readlane_b32 s40, v252, 4
	v_readlane_b32 s41, v252, 5
	s_lshl_b32 s27, s27, 1
	v_readlane_b32 s42, v252, 6
	v_readlane_b32 s43, v252, 7
	s_mov_b64 s[28:29], s[40:41]
	s_mov_b64 s[30:31], s[42:43]
	s_add_u32 s28, s28, s27
	s_addc_u32 s29, s29, 0
	s_and_b32 s30, s3, 0xffffffe0
	s_ashr_i32 s31, s30, 31
	s_lshl_b64 s[30:31], s[30:31], 11
	s_add_u32 s30, s24, s30
	s_addc_u32 s31, s25, s31
	v_lshl_add_u64 v[46:47], s[30:31], 0, v[2:3]
	global_load_dwordx4 v[14:17], v[46:47], off
	v_lshl_add_u64 v[30:31], s[28:29], 0, v[4:5]
	v_add_co_u32_e32 v18, vcc, s17, v30
	v_lshl_add_u64 v[48:49], s[30:31], 0, v[0:1]
	s_nop 0
	v_addc_co_u32_e32 v19, vcc, 0, v31, vcc
	global_load_dwordx4 v[18:21], v[18:19], off
	s_nop 0
	global_load_dwordx4 v[22:25], v[48:49], off
	global_load_dwordx4 v[26:29], v[46:47], off offset:64
	v_lshl_add_u64 v[50:51], v[30:31], 0, s[10:11]
	global_load_dwordx4 v[30:33], v[50:51], off offset:64
	global_load_dwordx4 v[34:37], v[48:49], off offset:64
	global_load_dwordx4 v[38:41], v[50:51], off offset:192
	global_load_dwordx4 v[42:45], v[46:47], off offset:128
	s_and_b64 vcc, exec, s[6:7]
	v_readlane_b32 s37, v252, 1
	v_readlane_b32 s38, v252, 2
	v_readlane_b32 s39, v252, 3
	s_waitcnt vmcnt(6)
	v_mfma_f32_16x16x32_bf16 v[14:17], v[14:17], v[18:21], 0
	s_waitcnt vmcnt(5)
	v_mfma_f32_16x16x32_bf16 v[18:21], v[22:25], v[18:21], 0
	global_load_dwordx4 v[22:25], v[50:51], off offset:128
	s_waitcnt vmcnt(4)
	v_mfma_f32_16x16x32_bf16 v[14:17], v[26:29], v[30:33], v[14:17]
	global_load_dwordx4 v[26:29], v[48:49], off offset:128
	s_waitcnt vmcnt(4)
	v_mfma_f32_16x16x32_bf16 v[18:21], v[34:37], v[30:33], v[18:21]
	global_load_dwordx4 v[30:33], v[46:47], off offset:192
	global_load_dwordx4 v[34:37], v[48:49], off offset:192
	s_waitcnt vmcnt(3)
	v_mfma_f32_16x16x32_bf16 v[14:17], v[42:45], v[22:25], v[14:17]
	s_waitcnt vmcnt(2)
	v_mfma_f32_16x16x32_bf16 v[18:21], v[26:29], v[22:25], v[18:21]
	s_waitcnt vmcnt(1)
	v_mfma_f32_16x16x32_bf16 v[14:17], v[30:33], v[38:41], v[14:17]
	s_waitcnt vmcnt(0)
	v_mfma_f32_16x16x32_bf16 v[18:21], v[34:37], v[38:41], v[18:21]
	s_nop 5
	ds_write_b128 v10, v[14:17]
	s_nop 0
	ds_write_b128 v10, v[18:21] offset:1024
	s_waitcnt lgkmcnt(0)
	s_barrier
	s_cbranch_vccnz .LBB0_721
	s_and_b32 s27, s13, 0x70
	v_or_b32_e32 v6, s27, v8
	s_add_i32 s27, s2, s3
	s_andn2_b32 s27, s27, 31
	v_or_b32_e32 v14, s27, v9
	v_lshl_or_b32 v6, v6, 11, v12
	v_ashrrev_i32_e32 v15, 31, v14
	v_lshl_add_u64 v[16:17], s[0:1], 0, v[6:7]
	v_lshlrev_b64 v[14:15], 1, v[14:15]
	v_lshl_add_u64 v[22:23], v[16:17], 0, v[14:15]
	v_lshl_add_u64 v[16:17], s[8:9], 0, v[6:7]
	v_lshl_add_u64 v[86:87], v[16:17], 0, v[14:15]
	global_load_dwordx4 v[14:17], v[22:23], off
	global_load_dwordx4 v[18:21], v[86:87], off
	ds_read_b128 v[22:25], v11
	ds_read_b128 v[26:29], v11 offset:1024
	ds_read_b128 v[30:33], v11 offset:2048
	ds_read_b128 v[34:37], v11 offset:3072
	ds_read_b128 v[38:41], v11 offset:4096
	ds_read_b128 v[42:45], v11 offset:5120
	ds_read_b128 v[46:49], v11 offset:6144
	ds_read_b128 v[50:53], v11 offset:7168
	ds_read_b128 v[54:57], v11 offset:8192
	ds_read_b128 v[58:61], v11 offset:9216
	ds_read_b128 v[62:65], v11 offset:10240
	ds_read_b128 v[66:69], v11 offset:11264
	ds_read_b128 v[70:73], v11 offset:12288
	ds_read_b128 v[74:77], v11 offset:13312
	ds_read_b128 v[78:81], v11 offset:14336
	ds_read_b128 v[82:85], v11 offset:15360
	s_waitcnt lgkmcnt(13)
	v_pk_add_f32 v[22:23], v[22:23], v[30:31]
	v_pk_add_f32 v[24:25], v[24:25], v[32:33]
	s_waitcnt lgkmcnt(11)
	v_pk_add_f32 v[22:23], v[22:23], v[38:39]
	v_pk_add_f32 v[26:27], v[26:27], v[34:35]
	s_waitcnt lgkmcnt(9)
	v_pk_add_f32 v[22:23], v[22:23], v[46:47]
	v_pk_add_f32 v[24:25], v[24:25], v[40:41]
	s_waitcnt lgkmcnt(7)
	v_pk_add_f32 v[22:23], v[22:23], v[54:55]
	v_pk_add_f32 v[26:27], v[26:27], v[42:43]
	s_waitcnt lgkmcnt(5)
	v_pk_add_f32 v[22:23], v[22:23], v[62:63]
	v_pk_add_f32 v[24:25], v[24:25], v[48:49]
	s_waitcnt lgkmcnt(3)
	v_pk_add_f32 v[22:23], v[22:23], v[70:71]
	v_pk_add_f32 v[26:27], v[26:27], v[50:51]
	s_waitcnt lgkmcnt(1)
	v_pk_add_f32 v[22:23], v[22:23], v[78:79]
	v_pk_add_f32 v[24:25], v[24:25], v[56:57]
	v_pk_add_f32 v[26:27], v[26:27], v[58:59]
	v_pk_add_f32 v[24:25], v[24:25], v[64:65]
	v_pk_add_f32 v[26:27], v[26:27], v[66:67]
	v_pk_add_f32 v[24:25], v[24:25], v[72:73]
	v_pk_add_f32 v[26:27], v[26:27], v[74:75]
	v_pk_add_f32 v[28:29], v[28:29], v[36:37]
	v_pk_add_f32 v[24:25], v[24:25], v[80:81]
	s_waitcnt lgkmcnt(0)
	v_pk_add_f32 v[26:27], v[26:27], v[82:83]
	v_pk_add_f32 v[28:29], v[28:29], v[44:45]
	s_waitcnt vmcnt(1)
	v_lshlrev_b32_e32 v6, 16, v14
	s_waitcnt vmcnt(0)
	v_lshlrev_b32_e32 v13, 16, v18
	v_and_b32_e32 v18, 0xffff0000, v18
	v_mul_f32_e32 v13, 0xbfb8aa3b, v13
	v_mul_f32_e32 v18, 0xbfb8aa3b, v18
	v_exp_f32_e32 v13, v13
	v_exp_f32_e32 v18, v18
	v_lshlrev_b32_e32 v31, 16, v19
	v_and_b32_e32 v19, 0xffff0000, v19
	v_lshlrev_b32_e32 v33, 16, v20
	v_and_b32_e32 v20, 0xffff0000, v20
	v_mul_f32_e32 v19, 0xbfb8aa3b, v19
	v_mul_f32_e32 v20, 0xbfb8aa3b, v20
	v_add_f32_e32 v13, 1.0, v13
	v_add_f32_e32 v18, 1.0, v18
	v_mul_f32_e32 v31, 0xbfb8aa3b, v31
	v_mul_f32_e32 v33, 0xbfb8aa3b, v33
	v_exp_f32_e32 v19, v19
	v_exp_f32_e32 v20, v20
	v_rcp_f32_e32 v13, v13
	v_rcp_f32_e32 v18, v18
	v_exp_f32_e32 v31, v31
	v_exp_f32_e32 v33, v33
	v_and_b32_e32 v14, 0xffff0000, v14
	v_add_f32_e32 v19, 1.0, v19
	v_add_f32_e32 v20, 1.0, v20
	v_fmac_f32_e32 v6, v22, v13
	v_fmac_f32_e32 v14, v23, v18
	v_lshlrev_b32_e32 v13, 16, v21
	v_lshlrev_b32_e32 v32, 16, v16
	v_add_f32_e32 v31, 1.0, v31
	v_add_f32_e32 v33, 1.0, v33
	v_rcp_f32_e32 v19, v19
	v_rcp_f32_e32 v20, v20
	v_cvt_pk_bf16_f32 v14, v6, v14
	v_and_b32_e32 v6, 0xffff0000, v16
	v_mul_f32_e32 v13, 0xbfb8aa3b, v13
	v_and_b32_e32 v16, 0xffff0000, v21
	v_rcp_f32_e32 v31, v31
	v_rcp_f32_e32 v33, v33
	v_exp_f32_e32 v13, v13
	v_mul_f32_e32 v16, 0xbfb8aa3b, v16
	v_exp_f32_e32 v18, v16
	v_lshlrev_b32_e32 v30, 16, v15
	v_and_b32_e32 v15, 0xffff0000, v15
	v_fmac_f32_e32 v15, v25, v19
	v_fmac_f32_e32 v6, v27, v20
	v_pk_add_f32 v[28:29], v[28:29], v[52:53]
	v_fmac_f32_e32 v30, v24, v31
	v_cvt_pk_bf16_f32 v15, v30, v15
	v_fmac_f32_e32 v32, v26, v33
	v_cvt_pk_bf16_f32 v16, v32, v6
	v_add_f32_e32 v6, 1.0, v13
	v_pk_add_f32 v[28:29], v[28:29], v[60:61]
	v_rcp_f32_e32 v6, v6
	v_add_f32_e32 v13, 1.0, v18
	v_pk_add_f32 v[28:29], v[28:29], v[68:69]
	v_rcp_f32_e32 v13, v13
	v_pk_add_f32 v[28:29], v[28:29], v[76:77]
	v_lshlrev_b32_e32 v18, 16, v17
	v_pk_add_f32 v[28:29], v[28:29], v[84:85]
	s_nop 0
	v_fmac_f32_e32 v18, v28, v6
	v_and_b32_e32 v6, 0xffff0000, v17
	v_fmac_f32_e32 v6, v29, v13
	v_cvt_pk_bf16_f32 v17, v18, v6
	global_store_dwordx4 v[86:87], v[14:17], off sc0 sc1
	s_branch .LBB0_721
.LBB0_724:
	s_waitcnt vmcnt(0)
	s_barrier
	s_mov_b64 s[0:1], exec
	v_readlane_b32 s2, v252, 9
	v_readlane_b32 s3, v252, 10
	s_and_b64 s[2:3], s[0:1], s[2:3]
	s_mov_b64 exec, s[2:3]
	s_cbranch_execz .LBB0_776
	v_readlane_b32 s30, v252, 11
	v_readlane_b32 s31, v252, 12
	v_readlane_b32 s32, v252, 48
	v_mov_b32_e32 v5, 1
	v_mov_b32_e32 v22, 0
	s_add_u32 s36, s30, 0x10000
	s_addc_u32 s37, s31, 0
	s_and_b32 s32, s32, 63
	s_lshl_b32 s32, s32, 8
	s_add_u32 s34, s30, 0x4000
	s_addc_u32 s35, s31, 0
	v_mov_b32_e32 v4, s32
	global_atomic_add v22, v5, s[36:37]
	s_cmpk_lg_u32 s86, 0x100
	s_cbranch_scc1 .Lxb4_global
	s_cmp_eq_u32 s99, 0
	s_cbranch_scc1 .Lxb4_nowb
	buffer_wbl2 sc1
	s_waitcnt vmcnt(0)

.Lxb4_global:
	v_readlane_b32 s30, v252, 11
	v_readlane_b32 s31, v252, 12
	v_readlane_b32 s32, v252, 13
	v_mov_b32_e32 v5, 1
	v_mov_b32_e32 v22, 0
	s_add_u32 s34, s30, 0x1400
	s_addc_u32 s35, s31, 0
	s_lshl_b32 s32, s32, 8
	s_add_u32 s40, s30, 0x3400
	s_addc_u32 s41, s31, 0
	v_mov_b32_e32 v4, s32
	s_mov_b32 s42, 0
	global_atomic_add v6, v4, v5, s[34:35] sc0
	s_mul_i32 s33, s86, 4
	s_mul_i32 s39, s98, 4
	s_waitcnt vmcnt(0)
	v_readfirstlane_b32 s38, v6
	v_mov_b32_e32 v7, s98
	s_add_i32 s38, s38, 1
	s_cmp_lg_u32 s38, s39
	s_cbranch_scc1 .Lxb4_spin
	buffer_wbl2 sc1
	s_waitcnt vmcnt(0)
	global_atomic_add v22, v7, s[40:41]

.Lxb4_end:
.LBB0_776:
	s_or_b64 exec, exec, s[0:1]
	v_readlane_b32 s8, v252, 0
	v_readlane_b32 s9, v252, 1
	v_readlane_b32 s10, v252, 2
	v_readlane_b32 s11, v252, 3
	v_readlane_b32 s12, v252, 4
	v_readlane_b32 s13, v252, 5
	v_readlane_b32 s14, v252, 6
	v_readlane_b32 s15, v252, 7
	s_mov_b64 s[8:9], s[12:13]
	s_mov_b64 s[10:11], s[14:15]
	s_add_u32 s3, s10, 0xb240000
	v_mov_b32_e32 v178, v176
	s_waitcnt lgkmcnt(0)
	s_barrier
	s_addc_u32 s38, s11, 0
	s_and_b64 vcc, exec, s[4:5]
	v_readfirstlane_b32 s11, v178
	s_cbranch_vccnz .LBB0_869
	s_ashr_i32 s39, s72, 31
	s_lshr_b32 s0, s39, 29
	s_add_i32 s2, s72, s0
	s_and_b32 s0, s2, -8
	s_sub_i32 s7, s72, s0
	s_cmp_gt_i32 s7, -1
	s_cbranch_scc0 .LBB0_779
	s_lshl_b32 s6, s7, 5
	s_cbranch_execz .LBB0_780
	s_branch .LBB0_781

.LBB0_849:
	s_or_b64 exec, exec, s[0:1]
	v_add_f32_e32 v128, 0, v132
	v_add_f32_e32 v128, v128, v133
	v_add_f32_e32 v128, v128, v134
	v_add_f32_e32 v128, v128, v138
	v_mov_b32_e32 v129, 0x358637bd
	v_fmac_f32_e32 v129, 0x3a800000, v128
	s_mov_b32 s0, 0xf800000
	v_mul_f32_e32 v128, 0x4f800000, v129
	v_cmp_gt_f32_e32 vcc, s0, v129
	v_mov_b32_e32 v181, s29
	s_nop 0
	v_cndmask_b32_e32 v128, v129, v128, vcc
	v_sqrt_f32_e32 v129, v128
	s_nop 0
	v_add_u32_e32 v130, -1, v129
	v_fma_f32 v131, -v130, v129, v128
	v_cmp_ge_f32_e64 s[0:1], 0, v131
	v_add_u32_e32 v131, 1, v129
	s_nop 0
	v_cndmask_b32_e64 v130, v129, v130, s[0:1]
	v_fma_f32 v129, -v131, v129, v128
	v_cmp_lt_f32_e64 s[0:1], 0, v129
	s_nop 1
	v_cndmask_b32_e64 v129, v130, v131, s[0:1]
	v_mul_f32_e32 v130, 0x37800000, v129
	v_cndmask_b32_e32 v129, v129, v130, vcc
	v_mov_b32_e32 v130, 0x260
	v_cmp_class_f32_e32 vcc, v128, v130
	s_nop 1
	v_cndmask_b32_e32 v128, v129, v128, vcc
	v_div_scale_f32 v129, s[0:1], v128, v128, 1.0
	v_rcp_f32_e32 v130, v129
	s_nop 0
	v_fma_f32 v131, -v129, v130, 1.0
	v_fmac_f32_e32 v130, v131, v130
	v_div_scale_f32 v131, vcc, 1.0, v128, 1.0
	v_mul_f32_e32 v132, v131, v130
	v_fma_f32 v133, -v129, v132, v131
	v_fmac_f32_e32 v132, v133, v130
	v_fma_f32 v129, -v129, v132, v131
	v_div_fmas_f32 v129, v129, v130, v132
	v_div_fixup_f32 v130, v129, v128, 1.0
	v_mad_u64_u32 v[128:129], s[0:1], v178, -12, v[136:137]
	ds_write_b32 v128, v130 offset:8192
	v_readlane_b32 s14, v252, 11
	v_readlane_b32 s15, v252, 12
	v_mov_b32_e32 v132, 0
	s_mov_b32 s16, 0
	s_add_u32 s14, s14, 0x10000
	s_addc_u32 s15, s15, 0

.Lgd4_ok:
.LBB0_850:
	s_or_b64 exec, exec, s[12:13]
	v_readlane_b32 s40, v252, 0
	v_readlane_b32 s44, v252, 4
	v_readlane_b32 s45, v252, 5
	v_readlane_b32 s46, v252, 6
	v_readlane_b32 s47, v252, 7
	s_mov_b64 s[12:13], s[44:45]
	s_lshl_b32 s11, s33, 5
	s_mov_b64 s[14:15], s[46:47]
	s_add_u32 s0, s14, 0x4160000
	s_addc_u32 s1, s15, 0
	s_lshl_b32 s12, s10, 8
	s_or_b32 s11, s12, s11
	v_add_u32_e32 v138, v181, v150
	v_readlane_b32 s41, v252, 1
	v_readlane_b32 s42, v252, 2
	v_readlane_b32 s43, v252, 3
	v_lshl_or_b32 v142, v148, 3, s11
	v_ashrrev_i32_e32 v139, 31, v138
	v_ashrrev_i32_e32 v143, 31, v142
	v_readlane_b32 s40, v252, 14
	v_lshlrev_b64 v[148:149], 10, v[138:139]
	v_readlane_b32 s41, v252, 15
	v_lshl_add_u64 v[140:141], v[148:149], 0, v[142:143]
	v_readlane_b32 s50, v252, 24
	v_readlane_b32 s51, v252, 25
	v_lshl_add_u64 v[154:155], v[140:141], 2, s[40:41]
	s_waitcnt lgkmcnt(0)
	s_barrier
	v_lshl_add_u64 v[146:147], v[142:143], 2, s[50:51]
	global_load_dwordx4 v[156:159], v[154:155], off nt
	global_load_dwordx4 v[132:135], v[146:147], off
	global_load_dwordx4 v[128:131], v[146:147], off offset:16
	global_load_dwordx4 v[160:163], v[154:155], off offset:16 nt
	v_lshl_add_u32 v182, v150, 2, 0
	ds_read_b32 v150, v182 offset:8192
	v_add_u32_e32 v144, 16, v138
	v_ashrrev_i32_e32 v145, 31, v144
	v_lshlrev_b64 v[144:145], 10, v[144:145]
	v_lshl_add_u64 v[166:167], v[144:145], 0, v[142:143]
	s_waitcnt lgkmcnt(0)
	v_pk_mul_f32 v[124:125], v[124:125], v[150:151] op_sel_hi:[1,0]
	v_pk_mul_f32 v[126:127], v[126:127], v[150:151] op_sel_hi:[1,0]
	v_pk_mul_f32 v[164:165], v[120:121], v[150:151] op_sel_hi:[1,0]
	v_pk_mul_f32 v[120:121], v[122:123], v[150:151] op_sel_hi:[1,0]
	v_lshl_add_u64 v[140:141], v[140:141], 1, s[0:1]
	v_lshl_add_u64 v[152:153], v[166:167], 2, s[40:41]
	v_lshl_add_u64 v[166:167], v[166:167], 1, s[0:1]
	v_readlane_b32 s42, v252, 16
	v_readlane_b32 s43, v252, 17
	v_readlane_b32 s44, v252, 18
	v_readlane_b32 s45, v252, 19
	v_readlane_b32 s46, v252, 20
	v_readlane_b32 s47, v252, 21
	v_readlane_b32 s48, v252, 22
	v_readlane_b32 s49, v252, 23
	v_readlane_b32 s52, v252, 26
	v_readlane_b32 s53, v252, 27
	v_readlane_b32 s54, v252, 28
	v_readlane_b32 s55, v252, 29
	s_waitcnt vmcnt(2)
	v_pk_fma_f32 v[122:123], v[134:135], v[126:127], v[158:159]
	v_pk_fma_f32 v[124:125], v[132:133], v[124:125], v[156:157]
	s_waitcnt vmcnt(0)
	v_pk_fma_f32 v[120:121], v[130:131], v[120:121], v[162:163]
	v_pk_fma_f32 v[126:127], v[128:129], v[164:165], v[160:161]
	v_cvt_pk_bf16_f32 v156, v124, v125
	v_cvt_pk_bf16_f32 v157, v122, v123
	v_mul_f32_e32 v125, v125, v125
	v_cvt_pk_bf16_f32 v158, v126, v127
	v_cvt_pk_bf16_f32 v159, v120, v121
	global_store_dwordx4 v[140:141], v[156:159], off
	global_load_dwordx4 v[158:161], v[152:153], off nt
	s_nop 0
	global_load_dwordx4 v[162:165], v[152:153], off offset:16 nt
	ds_read_b32 v168, v182 offset:8256
	v_add_u32_e32 v140, 32, v138
	v_ashrrev_i32_e32 v141, 31, v140
	v_lshlrev_b64 v[150:151], 10, v[140:141]
	v_lshl_add_u64 v[140:141], v[150:151], 0, v[142:143]
	s_waitcnt lgkmcnt(0)
	v_pk_mul_f32 v[170:171], v[116:117], v[168:169] op_sel_hi:[1,0]
	v_pk_mul_f32 v[116:117], v[118:119], v[168:169] op_sel_hi:[1,0]
	v_pk_mul_f32 v[172:173], v[112:113], v[168:169] op_sel_hi:[1,0]
	v_pk_mul_f32 v[112:113], v[114:115], v[168:169] op_sel_hi:[1,0]
	v_lshl_add_u64 v[156:157], v[140:141], 2, s[40:41]
	v_lshl_add_u64 v[140:141], v[140:141], 1, s[0:1]
	v_mul_f32_e32 v123, v123, v123
	v_mul_f32_e32 v127, v127, v127
	v_mul_f32_e32 v121, v121, v121
	v_fmac_f32_e32 v125, v124, v124
	v_fmac_f32_e32 v123, v122, v122
	v_fmac_f32_e32 v127, v126, v126
	v_fmac_f32_e32 v121, v120, v120
	v_add_f32_e32 v120, v125, v123
	v_add_f32_e32 v121, v127, v121
	v_add_f32_e32 v120, v120, v121
	s_waitcnt vmcnt(1)
	v_pk_fma_f32 v[116:117], v[134:135], v[116:117], v[160:161]
	v_pk_fma_f32 v[118:119], v[132:133], v[170:171], v[158:159]
	s_waitcnt vmcnt(0)
	v_pk_fma_f32 v[112:113], v[130:131], v[112:113], v[164:165]
	v_pk_fma_f32 v[114:115], v[128:129], v[172:173], v[162:163]
	v_cvt_pk_bf16_f32 v158, v118, v119
	v_cvt_pk_bf16_f32 v159, v116, v117
	s_nop 0
	v_cvt_pk_bf16_f32 v160, v114, v115
	v_cvt_pk_bf16_f32 v161, v112, v113
	global_store_dwordx4 v[166:167], v[158:161], off
	global_load_dwordx4 v[162:165], v[156:157], off nt
	s_nop 0
	global_load_dwordx4 v[166:169], v[156:157], off offset:16 nt
	ds_read_b32 v170, v182 offset:8320
	v_add_u32_e32 v158, 48, v138
	v_ashrrev_i32_e32 v159, 31, v158
	v_lshlrev_b64 v[158:159], 10, v[158:159]
	v_lshl_add_u64 v[174:175], v[158:159], 0, v[142:143]
	s_waitcnt lgkmcnt(0)
	v_pk_mul_f32 v[172:173], v[108:109], v[170:171] op_sel_hi:[1,0]
	v_pk_mul_f32 v[108:109], v[110:111], v[170:171] op_sel_hi:[1,0]
	v_pk_mul_f32 v[184:185], v[104:105], v[170:171] op_sel_hi:[1,0]
	v_pk_mul_f32 v[104:105], v[106:107], v[170:171] op_sel_hi:[1,0]
	v_lshl_add_u64 v[160:161], v[174:175], 2, s[40:41]
	v_lshl_add_u64 v[174:175], v[174:175], 1, s[0:1]
	s_waitcnt vmcnt(1)
	v_pk_fma_f32 v[108:109], v[134:135], v[108:109], v[164:165]
	v_pk_fma_f32 v[110:111], v[132:133], v[172:173], v[162:163]
	s_waitcnt vmcnt(0)
	v_pk_fma_f32 v[104:105], v[130:131], v[104:105], v[168:169]
	v_pk_fma_f32 v[106:107], v[128:129], v[184:185], v[166:167]
	v_cvt_pk_bf16_f32 v162, v110, v111
	v_cvt_pk_bf16_f32 v163, v108, v109
	s_nop 0
	v_cvt_pk_bf16_f32 v164, v106, v107
	v_cvt_pk_bf16_f32 v165, v104, v105
	global_store_dwordx4 v[140:141], v[162:165], off
	global_load_dwordx4 v[166:169], v[160:161], off nt
	global_load_dwordx4 v[170:173], v[160:161], off offset:16 nt
	ds_read_b32 v184, v182 offset:8384
	v_add_u32_e32 v140, 0x80, v138
	v_ashrrev_i32_e32 v141, 31, v140
	v_lshlrev_b64 v[162:163], 10, v[140:141]
	v_lshl_add_u64 v[140:141], v[162:163], 0, v[142:143]
	s_waitcnt lgkmcnt(0)
	v_pk_mul_f32 v[186:187], v[100:101], v[184:185] op_sel_hi:[1,0]
	v_pk_mul_f32 v[100:101], v[102:103], v[184:185] op_sel_hi:[1,0]
	v_pk_mul_f32 v[188:189], v[96:97], v[184:185] op_sel_hi:[1,0]
	v_pk_mul_f32 v[96:97], v[98:99], v[184:185] op_sel_hi:[1,0]
	v_lshl_add_u64 v[164:165], v[140:141], 2, s[40:41]
	v_lshl_add_u64 v[140:141], v[140:141], 1, s[0:1]
	s_waitcnt vmcnt(1)
	v_pk_fma_f32 v[100:101], v[134:135], v[100:101], v[168:169]
	v_pk_fma_f32 v[102:103], v[132:133], v[186:187], v[166:167]
	s_waitcnt vmcnt(0)
	v_pk_fma_f32 v[96:97], v[130:131], v[96:97], v[172:173]
	v_pk_fma_f32 v[98:99], v[128:129], v[188:189], v[170:171]
	v_cvt_pk_bf16_f32 v166, v102, v103
	v_cvt_pk_bf16_f32 v167, v100, v101
	s_nop 0
	v_cvt_pk_bf16_f32 v168, v98, v99
	v_cvt_pk_bf16_f32 v169, v96, v97
	global_store_dwordx4 v[174:175], v[166:169], off
	global_load_dwordx4 v[170:173], v[164:165], off nt
	global_load_dwordx4 v[184:187], v[164:165], off offset:16 nt
	ds_read_b32 v174, v182 offset:8704
	v_add_u32_e32 v166, 0x90, v138
	v_ashrrev_i32_e32 v167, 31, v166
	v_lshlrev_b64 v[166:167], 10, v[166:167]
	v_lshl_add_u64 v[192:193], v[166:167], 0, v[142:143]
	s_waitcnt lgkmcnt(0)
	v_pk_mul_f32 v[188:189], v[92:93], v[174:175] op_sel_hi:[1,0]
	v_pk_mul_f32 v[92:93], v[94:95], v[174:175] op_sel_hi:[1,0]
	v_pk_mul_f32 v[190:191], v[88:89], v[174:175] op_sel_hi:[1,0]
	v_pk_mul_f32 v[88:89], v[90:91], v[174:175] op_sel_hi:[1,0]
	v_lshl_add_u64 v[168:169], v[192:193], 2, s[40:41]
	s_waitcnt vmcnt(1)
	v_pk_fma_f32 v[92:93], v[134:135], v[92:93], v[172:173]
	v_pk_fma_f32 v[94:95], v[132:133], v[188:189], v[170:171]
	s_waitcnt vmcnt(0)
	v_pk_fma_f32 v[88:89], v[130:131], v[88:89], v[186:187]
	v_pk_fma_f32 v[90:91], v[128:129], v[190:191], v[184:185]
	v_cvt_pk_bf16_f32 v170, v94, v95
	v_cvt_pk_bf16_f32 v171, v92, v93
	s_nop 0
	v_cvt_pk_bf16_f32 v172, v90, v91
	v_cvt_pk_bf16_f32 v173, v88, v89
	global_store_dwordx4 v[140:141], v[170:173], off
	global_load_dwordx4 v[184:187], v[168:169], off nt
	global_load_dwordx4 v[188:191], v[168:169], off offset:16 nt
	ds_read_b32 v174, v182 offset:8768
	v_add_u32_e32 v140, 0xa0, v138
	v_ashrrev_i32_e32 v141, 31, v140
	v_lshlrev_b64 v[170:171], 10, v[140:141]
	v_lshl_add_u64 v[194:195], v[170:171], 0, v[142:143]
	v_lshl_add_u64 v[140:141], v[192:193], 1, s[0:1]
	s_waitcnt lgkmcnt(0)
	v_pk_mul_f32 v[192:193], v[84:85], v[174:175] op_sel_hi:[1,0]
	v_pk_mul_f32 v[84:85], v[86:87], v[174:175] op_sel_hi:[1,0]
	v_pk_mul_f32 v[196:197], v[80:81], v[174:175] op_sel_hi:[1,0]
	v_pk_mul_f32 v[80:81], v[82:83], v[174:175] op_sel_hi:[1,0]
	v_lshl_add_u64 v[172:173], v[194:195], 2, s[40:41]
	v_add_u32_e32 v138, 0xb0, v138
	v_ashrrev_i32_e32 v139, 31, v138
	v_lshl_add_u64 v[194:195], v[194:195], 1, s[0:1]
	s_waitcnt vmcnt(1)
	v_pk_fma_f32 v[84:85], v[134:135], v[84:85], v[186:187]
	v_pk_fma_f32 v[86:87], v[132:133], v[192:193], v[184:185]
	s_waitcnt vmcnt(0)
	v_pk_fma_f32 v[80:81], v[130:131], v[80:81], v[190:191]
	v_pk_fma_f32 v[82:83], v[128:129], v[196:197], v[188:189]
	v_cvt_pk_bf16_f32 v184, v86, v87
	v_cvt_pk_bf16_f32 v185, v84, v85
	s_nop 0
	v_cvt_pk_bf16_f32 v186, v82, v83
	v_cvt_pk_bf16_f32 v187, v80, v81
	global_store_dwordx4 v[140:141], v[184:187], off
	global_load_dwordx4 v[184:187], v[172:173], off nt
	s_nop 0
	global_load_dwordx4 v[188:191], v[172:173], off offset:16 nt
	ds_read_b32 v192, v182 offset:8832
	v_lshlrev_b64 v[140:141], 10, v[138:139]
	v_lshl_add_u64 v[196:197], v[140:141], 0, v[142:143]
	v_lshl_add_u64 v[174:175], v[196:197], 2, s[40:41]
	s_waitcnt lgkmcnt(0)
	v_pk_mul_f32 v[76:77], v[76:77], v[192:193] op_sel_hi:[1,0]
	v_pk_mul_f32 v[78:79], v[78:79], v[192:193] op_sel_hi:[1,0]
	v_pk_mul_f32 v[198:199], v[72:73], v[192:193] op_sel_hi:[1,0]
	v_pk_mul_f32 v[72:73], v[74:75], v[192:193] op_sel_hi:[1,0]
	v_lshl_add_u64 v[192:193], v[196:197], 1, s[0:1]
	s_waitcnt vmcnt(1)
	v_pk_fma_f32 v[78:79], v[134:135], v[78:79], v[186:187]
	v_pk_fma_f32 v[138:139], v[132:133], v[76:77], v[184:185]
	s_waitcnt vmcnt(0)
	v_pk_fma_f32 v[72:73], v[130:131], v[72:73], v[190:191]
	v_pk_fma_f32 v[74:75], v[128:129], v[198:199], v[188:189]
	v_cvt_pk_bf16_f32 v184, v138, v139
	v_cvt_pk_bf16_f32 v185, v78, v79
	s_nop 0
	v_cvt_pk_bf16_f32 v186, v74, v75
	v_cvt_pk_bf16_f32 v187, v72, v73
	global_store_dwordx4 v[194:195], v[184:187], off
	global_load_dwordx4 v[184:187], v[174:175], off nt
	s_nop 0
	global_load_dwordx4 v[188:191], v[174:175], off offset:16 nt
	ds_read_b32 v76, v182 offset:8896
	s_waitcnt lgkmcnt(0)
	v_pk_mul_f32 v[64:65], v[64:65], v[76:77] op_sel_hi:[1,0]
	v_pk_mul_f32 v[66:67], v[66:67], v[76:77] op_sel_hi:[1,0]
	v_pk_mul_f32 v[56:57], v[56:57], v[76:77] op_sel_hi:[1,0]
	v_pk_mul_f32 v[58:59], v[58:59], v[76:77] op_sel_hi:[1,0]
	s_waitcnt vmcnt(1)
	v_pk_fma_f32 v[134:135], v[134:135], v[66:67], v[186:187]
	v_pk_fma_f32 v[132:133], v[132:133], v[64:65], v[184:185]
	s_waitcnt vmcnt(0)
	v_pk_fma_f32 v[76:77], v[130:131], v[58:59], v[190:191]
	v_pk_fma_f32 v[128:129], v[128:129], v[56:57], v[188:189]
	v_cvt_pk_bf16_f32 v56, v132, v133
	v_cvt_pk_bf16_f32 v57, v134, v135
	v_or_b32_e32 v130, 0x80, v142
	v_cvt_pk_bf16_f32 v58, v128, v129
	v_cvt_pk_bf16_f32 v59, v76, v77
	global_store_dwordx4 v[192:193], v[56:59], off
	global_load_dwordx4 v[184:187], v[154:155], off offset:512 nt
	global_load_dwordx4 v[64:67], v[146:147], off offset:512
	s_nop 0
	global_load_dwordx4 v[56:59], v[146:147], off offset:528
	global_load_dwordx4 v[188:191], v[154:155], off offset:528 nt
	ds_read_b32 v146, v182 offset:8192
	v_ashrrev_i32_e32 v131, 31, v130
	v_lshl_add_u64 v[142:143], v[148:149], 0, v[130:131]
	v_lshl_add_u64 v[142:143], v[142:143], 1, s[0:1]
	v_lshl_add_u64 v[144:145], v[144:145], 0, v[130:131]
	s_waitcnt lgkmcnt(0)
	v_pk_mul_f32 v[68:69], v[68:69], v[146:147] op_sel_hi:[1,0]
	v_pk_mul_f32 v[70:71], v[70:71], v[146:147] op_sel_hi:[1,0]
	v_pk_mul_f32 v[148:149], v[60:61], v[146:147] op_sel_hi:[1,0]
	v_pk_mul_f32 v[60:61], v[62:63], v[146:147] op_sel_hi:[1,0]
	v_lshl_add_u64 v[150:151], v[150:151], 0, v[130:131]
	v_lshl_add_u64 v[150:151], v[150:151], 1, s[0:1]
	s_waitcnt vmcnt(2)
	v_pk_fma_f32 v[62:63], v[66:67], v[70:71], v[186:187]
	v_pk_fma_f32 v[68:69], v[64:65], v[68:69], v[184:185]
	s_waitcnt vmcnt(0)
	v_pk_fma_f32 v[60:61], v[58:59], v[60:61], v[190:191]
	v_pk_fma_f32 v[70:71], v[56:57], v[148:149], v[188:189]
	v_cvt_pk_bf16_f32 v146, v68, v69
	v_cvt_pk_bf16_f32 v147, v62, v63
	v_lshl_add_u64 v[184:185], v[144:145], 1, s[0:1]
	v_cvt_pk_bf16_f32 v148, v70, v71
	v_cvt_pk_bf16_f32 v149, v60, v61
	global_store_dwordx4 v[142:143], v[146:149], off
	global_load_dwordx4 v[146:149], v[152:153], off offset:512 nt
	s_nop 0
	global_load_dwordx4 v[152:155], v[152:153], off offset:528 nt
	ds_read_b32 v142, v182 offset:8256
	v_mul_f32_e32 v69, v69, v69
	v_mul_f32_e32 v63, v63, v63
	v_mul_f32_e32 v71, v71, v71
	v_mul_f32_e32 v61, v61, v61
	s_waitcnt lgkmcnt(0)
	v_pk_mul_f32 v[144:145], v[52:53], v[142:143] op_sel_hi:[1,0]
	v_pk_mul_f32 v[52:53], v[54:55], v[142:143] op_sel_hi:[1,0]
	v_pk_mul_f32 v[186:187], v[48:49], v[142:143] op_sel_hi:[1,0]
	v_pk_mul_f32 v[48:49], v[50:51], v[142:143] op_sel_hi:[1,0]
	v_fmac_f32_e32 v69, v68, v68
	v_fmac_f32_e32 v63, v62, v62
	v_fmac_f32_e32 v71, v70, v70
	v_fmac_f32_e32 v61, v60, v60
	v_add_f32_e32 v60, v69, v63
	v_add_f32_e32 v61, v71, v61
	v_add_f32_e32 v60, v120, v60
	v_add_f32_e32 v60, v61, v60
	ds_bpermute_b32 v61, v137, v60
	v_lshl_add_u64 v[68:69], v[140:141], 0, v[130:131]
	s_waitcnt lgkmcnt(0)
	v_add_f32_e32 v60, v60, v61
	ds_bpermute_b32 v61, v180, v60
	s_waitcnt vmcnt(1)
	v_pk_fma_f32 v[52:53], v[66:67], v[52:53], v[148:149]
	v_pk_fma_f32 v[54:55], v[64:65], v[144:145], v[146:147]
	s_waitcnt vmcnt(0)
	v_pk_fma_f32 v[48:49], v[58:59], v[48:49], v[154:155]
	v_pk_fma_f32 v[50:51], v[56:57], v[186:187], v[152:153]
	v_cvt_pk_bf16_f32 v142, v54, v55
	v_cvt_pk_bf16_f32 v143, v52, v53
	s_nop 0
	v_cvt_pk_bf16_f32 v144, v50, v51
	v_cvt_pk_bf16_f32 v145, v48, v49
	global_store_dwordx4 v[184:185], v[142:145], off
	global_load_dwordx4 v[142:145], v[156:157], off offset:512 nt
	s_nop 0
	global_load_dwordx4 v[146:149], v[156:157], off offset:528 nt
	ds_read_b32 v152, v182 offset:8320
	s_waitcnt lgkmcnt(0)
	v_pk_mul_f32 v[154:155], v[44:45], v[152:153] op_sel_hi:[1,0]
	v_pk_mul_f32 v[44:45], v[46:47], v[152:153] op_sel_hi:[1,0]
	v_pk_mul_f32 v[156:157], v[40:41], v[152:153] op_sel_hi:[1,0]
	v_pk_mul_f32 v[40:41], v[42:43], v[152:153] op_sel_hi:[1,0]
	v_lshl_add_u64 v[152:153], v[158:159], 0, v[130:131]
	v_lshl_add_u64 v[152:153], v[152:153], 1, s[0:1]
	s_waitcnt vmcnt(1)
	v_pk_fma_f32 v[44:45], v[66:67], v[44:45], v[144:145]
	v_pk_fma_f32 v[46:47], v[64:65], v[154:155], v[142:143]
	s_waitcnt vmcnt(0)
	v_pk_fma_f32 v[40:41], v[58:59], v[40:41], v[148:149]
	v_pk_fma_f32 v[42:43], v[56:57], v[156:157], v[146:147]
	v_cvt_pk_bf16_f32 v142, v46, v47
	v_cvt_pk_bf16_f32 v143, v44, v45
	s_nop 0
	v_cvt_pk_bf16_f32 v144, v42, v43
	v_cvt_pk_bf16_f32 v145, v40, v41
	global_store_dwordx4 v[150:151], v[142:145], off
	global_load_dwordx4 v[142:145], v[160:161], off offset:512 nt
	s_nop 0
	global_load_dwordx4 v[146:149], v[160:161], off offset:528 nt
	ds_read_b32 v150, v182 offset:8384
	s_waitcnt lgkmcnt(0)
	v_pk_mul_f32 v[154:155], v[36:37], v[150:151] op_sel_hi:[1,0]
	v_pk_mul_f32 v[36:37], v[38:39], v[150:151] op_sel_hi:[1,0]
	v_pk_mul_f32 v[156:157], v[32:33], v[150:151] op_sel_hi:[1,0]
	v_pk_mul_f32 v[32:33], v[34:35], v[150:151] op_sel_hi:[1,0]
	s_waitcnt vmcnt(1)
	v_pk_fma_f32 v[36:37], v[66:67], v[36:37], v[144:145]
	v_pk_fma_f32 v[38:39], v[64:65], v[154:155], v[142:143]
	s_waitcnt vmcnt(0)
	v_pk_fma_f32 v[32:33], v[58:59], v[32:33], v[148:149]
	v_pk_fma_f32 v[34:35], v[56:57], v[156:157], v[146:147]
	v_cvt_pk_bf16_f32 v142, v38, v39
	v_cvt_pk_bf16_f32 v143, v36, v37
	s_nop 0
	v_cvt_pk_bf16_f32 v144, v34, v35
	v_cvt_pk_bf16_f32 v145, v32, v33
	global_store_dwordx4 v[152:153], v[142:145], off
	global_load_dwordx4 v[142:145], v[164:165], off offset:512 nt
	s_nop 0
	global_load_dwordx4 v[146:149], v[164:165], off offset:528 nt
	ds_read_b32 v150, v182 offset:8704
	v_lshl_add_u64 v[152:153], v[162:163], 0, v[130:131]
	v_lshl_add_u64 v[152:153], v[152:153], 1, s[0:1]
	s_waitcnt lgkmcnt(0)
	v_pk_mul_f32 v[154:155], v[28:29], v[150:151] op_sel_hi:[1,0]
	v_pk_mul_f32 v[28:29], v[30:31], v[150:151] op_sel_hi:[1,0]
	v_pk_mul_f32 v[156:157], v[24:25], v[150:151] op_sel_hi:[1,0]
	v_pk_mul_f32 v[24:25], v[26:27], v[150:151] op_sel_hi:[1,0]
	s_waitcnt vmcnt(1)
	v_pk_fma_f32 v[28:29], v[66:67], v[28:29], v[144:145]
	v_pk_fma_f32 v[30:31], v[64:65], v[154:155], v[142:143]
	s_waitcnt vmcnt(0)
	v_pk_fma_f32 v[24:25], v[58:59], v[24:25], v[148:149]
	v_pk_fma_f32 v[26:27], v[56:57], v[156:157], v[146:147]
	v_cvt_pk_bf16_f32 v142, v30, v31
	v_cvt_pk_bf16_f32 v143, v28, v29
	s_nop 0
	v_cvt_pk_bf16_f32 v144, v26, v27
	v_cvt_pk_bf16_f32 v145, v24, v25
	global_store_dwordx4 v[152:153], v[142:145], off
	global_load_dwordx4 v[142:145], v[168:169], off offset:512 nt
	s_nop 0
	global_load_dwordx4 v[146:149], v[168:169], off offset:528 nt
	ds_read_b32 v150, v182 offset:8768
	v_lshl_add_u64 v[152:153], v[166:167], 0, v[130:131]
	v_lshl_add_u64 v[152:153], v[152:153], 1, s[0:1]
	s_waitcnt lgkmcnt(0)
	v_pk_mul_f32 v[154:155], v[20:21], v[150:151] op_sel_hi:[1,0]
	v_pk_mul_f32 v[20:21], v[22:23], v[150:151] op_sel_hi:[1,0]
	v_pk_mul_f32 v[156:157], v[16:17], v[150:151] op_sel_hi:[1,0]
	v_pk_mul_f32 v[16:17], v[18:19], v[150:151] op_sel_hi:[1,0]
	s_waitcnt vmcnt(1)
	v_pk_fma_f32 v[20:21], v[66:67], v[20:21], v[144:145]
	v_pk_fma_f32 v[22:23], v[64:65], v[154:155], v[142:143]
	s_waitcnt vmcnt(0)
	v_pk_fma_f32 v[16:17], v[58:59], v[16:17], v[148:149]
	v_pk_fma_f32 v[18:19], v[56:57], v[156:157], v[146:147]
	v_cvt_pk_bf16_f32 v142, v22, v23
	v_cvt_pk_bf16_f32 v143, v20, v21
	s_nop 0
	v_cvt_pk_bf16_f32 v144, v18, v19
	v_cvt_pk_bf16_f32 v145, v16, v17
	global_store_dwordx4 v[152:153], v[142:145], off
	global_load_dwordx4 v[142:145], v[172:173], off offset:512 nt
	s_nop 0
	global_load_dwordx4 v[146:149], v[172:173], off offset:528 nt
	ds_read_b32 v150, v182 offset:8832
	v_lshl_add_u64 v[152:153], v[170:171], 0, v[130:131]
	v_lshl_add_u64 v[152:153], v[152:153], 1, s[0:1]
	s_waitcnt lgkmcnt(0)
	v_pk_mul_f32 v[154:155], v[12:13], v[150:151] op_sel_hi:[1,0]
	v_pk_mul_f32 v[12:13], v[14:15], v[150:151] op_sel_hi:[1,0]
	v_pk_mul_f32 v[156:157], v[8:9], v[150:151] op_sel_hi:[1,0]
	v_pk_mul_f32 v[8:9], v[10:11], v[150:151] op_sel_hi:[1,0]
	s_waitcnt vmcnt(1)
	v_pk_fma_f32 v[12:13], v[66:67], v[12:13], v[144:145]
	v_pk_fma_f32 v[14:15], v[64:65], v[154:155], v[142:143]
	s_waitcnt vmcnt(0)
	v_pk_fma_f32 v[8:9], v[58:59], v[8:9], v[148:149]
	v_pk_fma_f32 v[10:11], v[56:57], v[156:157], v[146:147]
	v_cvt_pk_bf16_f32 v142, v14, v15
	v_cvt_pk_bf16_f32 v143, v12, v13
	s_nop 0
	v_cvt_pk_bf16_f32 v144, v10, v11
	v_cvt_pk_bf16_f32 v145, v8, v9
	global_store_dwordx4 v[152:153], v[142:145], off
	global_load_dwordx4 v[142:145], v[174:175], off offset:512 nt
	s_nop 0
	global_load_dwordx4 v[146:149], v[174:175], off offset:528 nt
	ds_read_b32 v62, v182 offset:8896
	s_waitcnt lgkmcnt(0)
	v_pk_mul_f32 v[70:71], v[4:5], v[62:63] op_sel_hi:[1,0]
	v_pk_mul_f32 v[4:5], v[6:7], v[62:63] op_sel_hi:[1,0]
	v_pk_mul_f32 v[120:121], v[0:1], v[62:63] op_sel_hi:[1,0]
	v_pk_mul_f32 v[0:1], v[2:3], v[62:63] op_sel_hi:[1,0]
	v_lshl_add_u64 v[62:63], v[68:69], 1, s[0:1]
	s_waitcnt vmcnt(1)
	v_pk_fma_f32 v[4:5], v[66:67], v[4:5], v[144:145]
	v_pk_fma_f32 v[6:7], v[64:65], v[70:71], v[142:143]
	s_waitcnt vmcnt(0)
	v_pk_fma_f32 v[0:1], v[58:59], v[0:1], v[148:149]
	v_pk_fma_f32 v[2:3], v[56:57], v[120:121], v[146:147]
	v_cvt_pk_bf16_f32 v56, v6, v7
	v_cvt_pk_bf16_f32 v57, v4, v5
	s_nop 0
	v_cvt_pk_bf16_f32 v58, v2, v3
	v_cvt_pk_bf16_f32 v59, v0, v1
	global_store_dwordx4 v[62:63], v[56:59], off
	s_and_saveexec_b64 s[0:1], s[6:7]
	s_lshl_b32 s11, s2, 10
	s_add_i32 s11, s28, s11
	v_lshl_add_u32 v56, v179, 4, s11
	v_add_f32_e32 v57, v60, v61
	ds_write_b32 v56, v57
	s_or_b64 exec, exec, s[0:1]
	v_mul_f32_e32 v56, v119, v119
	v_mul_f32_e32 v57, v117, v117
	v_fmac_f32_e32 v56, v118, v118
	v_fmac_f32_e32 v57, v116, v116
	v_add_f32_e32 v56, v56, v57
	v_mul_f32_e32 v57, v115, v115
	v_mul_f32_e32 v58, v113, v113
	v_fmac_f32_e32 v57, v114, v114
	v_fmac_f32_e32 v58, v112, v112
	v_mul_f32_e32 v55, v55, v55
	v_mul_f32_e32 v53, v53, v53
	v_add_f32_e32 v57, v57, v58
	v_fmac_f32_e32 v55, v54, v54
	v_fmac_f32_e32 v53, v52, v52
	v_mul_f32_e32 v51, v51, v51
	v_mul_f32_e32 v49, v49, v49
	v_add_f32_e32 v56, v56, v57
	v_add_f32_e32 v52, v55, v53
	v_fmac_f32_e32 v51, v50, v50
	v_fmac_f32_e32 v49, v48, v48
	v_add_f32_e32 v52, v56, v52
	v_add_f32_e32 v48, v51, v49
	v_add_f32_e32 v48, v48, v52
	ds_bpermute_b32 v49, v137, v48
	s_waitcnt lgkmcnt(0)
	v_add_f32_e32 v48, v48, v49
	ds_bpermute_b32 v49, v180, v48
	s_and_saveexec_b64 s[0:1], s[6:7]
	s_cbranch_execz .LBB0_854
	s_lshl_b32 s11, s2, 10
	s_add_i32 s11, s28, s11
	v_lshl_add_u32 v50, v179, 4, s11
	s_waitcnt lgkmcnt(0)
	v_add_f32_e32 v48, v48, v49
	ds_write_b32 v50, v48 offset:256

.LBB0_873:
	s_lshl_b32 s0, s37, 15
	s_and_b32 s0, s0, 0x38000
	s_add_u32 s0, s3, s0
	s_addc_u32 s1, s38, 0
	s_lshl_b32 s16, s37, 2
	s_andn2_b32 s16, s16, 31
	s_ashr_i32 s17, s16, 31
	s_lshl_b64 s[16:17], s[16:17], 11
	s_add_u32 s16, s22, s16
	s_addc_u32 s17, s23, s17
	v_lshl_add_u64 v[54:55], s[16:17], 0, v[4:5]
	global_load_dwordx4 v[16:19], v[54:55], off sc1
	v_lshl_add_u64 v[38:39], s[0:1], 0, v[6:7]
	v_add_co_u32_e32 v20, vcc, s33, v38
	v_lshl_add_u64 v[56:57], s[16:17], 0, v[2:3]
	s_nop 0
	v_addc_co_u32_e32 v21, vcc, 0, v39, vcc
	global_load_dwordx4 v[20:23], v[20:21], off sc1
	s_nop 0
	global_load_dwordx4 v[24:27], v[56:57], off sc1
	global_load_dwordx4 v[28:31], v[54:55], off offset:64 sc1
	v_lshl_add_u64 v[58:59], v[38:39], 0, s[12:13]
	global_load_dwordx4 v[38:41], v[58:59], off offset:64 sc1
	global_load_dwordx4 v[42:45], v[56:57], off offset:64 sc1
	global_load_dwordx4 v[46:49], v[58:59], off offset:192 sc1
	global_load_dwordx4 v[50:53], v[54:55], off offset:128 sc1
	s_and_b64 vcc, exec, s[8:9]
	s_waitcnt vmcnt(6)
	v_mfma_f32_16x16x32_bf16 v[16:19], v[16:19], v[20:23], 0
	s_waitcnt vmcnt(5)
	v_mfma_f32_16x16x32_bf16 v[20:23], v[24:27], v[20:23], 0
	global_load_dwordx4 v[24:27], v[58:59], off offset:128 sc1
	s_waitcnt vmcnt(4)
	v_mfma_f32_16x16x32_bf16 v[16:19], v[28:31], v[38:41], v[16:19]
	global_load_dwordx4 v[28:31], v[56:57], off offset:128 sc1
	s_waitcnt vmcnt(4)
	v_mfma_f32_16x16x32_bf16 v[20:23], v[42:45], v[38:41], v[20:23]
	global_load_dwordx4 v[38:41], v[54:55], off offset:192 sc1
	global_load_dwordx4 v[42:45], v[56:57], off offset:192 sc1
	s_waitcnt vmcnt(3)
	v_mfma_f32_16x16x32_bf16 v[16:19], v[50:53], v[24:27], v[16:19]
	s_waitcnt vmcnt(2)
	v_mfma_f32_16x16x32_bf16 v[20:23], v[28:31], v[24:27], v[20:23]
	s_waitcnt vmcnt(1)
	v_mfma_f32_16x16x32_bf16 v[16:19], v[38:41], v[46:49], v[16:19]
	s_waitcnt vmcnt(0)
	v_mfma_f32_16x16x32_bf16 v[20:23], v[42:45], v[46:49], v[20:23]
	s_nop 5
	ds_write_b128 v11, v[16:19]
	s_nop 0
	ds_write_b128 v11, v[20:23] offset:1024
	s_waitcnt lgkmcnt(0)
	s_barrier
	s_cbranch_vccnz .LBB0_872
	ds_read_b128 v[16:19], v13 offset:2048
	ds_read_b128 v[20:23], v13
	ds_read_b128 v[24:27], v13 offset:1024
	ds_read_b128 v[28:31], v13 offset:3072
	ds_read_b128 v[38:41], v13 offset:4096
	v_cmp_lt_i32_e32 vcc, v32, v33
	s_waitcnt lgkmcnt(3)
	v_pk_add_f32 v[22:23], v[22:23], v[18:19]
	v_pk_add_f32 v[42:43], v[20:21], v[16:17]
	ds_read_b128 v[16:19], v13 offset:5120
	s_waitcnt lgkmcnt(2)
	v_pk_add_f32 v[26:27], v[26:27], v[30:31]
	s_waitcnt lgkmcnt(1)
	v_pk_add_f32 v[30:31], v[22:23], v[40:41]
	ds_read_b128 v[20:23], v13 offset:6144
	v_pk_add_f32 v[28:29], v[24:25], v[28:29]
	v_pk_add_f32 v[38:39], v[42:43], v[38:39]
	s_waitcnt lgkmcnt(1)
	v_pk_add_f32 v[40:41], v[26:27], v[18:19]
	ds_read_b128 v[24:27], v13 offset:7168
	v_pk_add_f32 v[28:29], v[28:29], v[16:17]
	s_waitcnt lgkmcnt(1)
	v_pk_add_f32 v[30:31], v[30:31], v[22:23]
	ds_read_b128 v[16:19], v13 offset:8192
	v_pk_add_f32 v[38:39], v[38:39], v[20:21]
	ds_read_b128 v[20:23], v13 offset:9216
	s_waitcnt lgkmcnt(2)
	v_pk_add_f32 v[40:41], v[40:41], v[26:27]
	v_pk_add_f32 v[28:29], v[28:29], v[24:25]
	ds_read_b128 v[24:27], v13 offset:10240
	s_waitcnt lgkmcnt(2)
	v_pk_add_f32 v[30:31], v[30:31], v[18:19]
	v_pk_add_f32 v[38:39], v[38:39], v[16:17]
	s_waitcnt lgkmcnt(1)
	v_pk_add_f32 v[40:41], v[40:41], v[22:23]
	ds_read_b128 v[16:19], v13 offset:11264
	v_pk_add_f32 v[28:29], v[28:29], v[20:21]
	ds_read_b128 v[20:23], v13 offset:12288
	s_waitcnt lgkmcnt(2)
	v_pk_add_f32 v[26:27], v[30:31], v[26:27]
	v_pk_add_f32 v[30:31], v[38:39], v[24:25]
	s_waitcnt lgkmcnt(1)
	v_pk_add_f32 v[38:39], v[40:41], v[18:19]
	v_pk_add_f32 v[40:41], v[28:29], v[16:17]
	ds_read_b128 v[16:19], v13 offset:13312
	s_waitcnt lgkmcnt(1)
	v_pk_add_f32 v[42:43], v[26:27], v[22:23]
	ds_read_b128 v[22:25], v13 offset:14336
	ds_read_b128 v[26:29], v13 offset:15360
	v_pk_add_f32 v[30:31], v[30:31], v[20:21]
	s_waitcnt lgkmcnt(2)
	v_pk_add_f32 v[18:19], v[38:39], v[18:19]
	v_pk_add_f32 v[16:17], v[40:41], v[16:17]
	s_waitcnt lgkmcnt(1)
	v_pk_add_f32 v[20:21], v[42:43], v[24:25]
	v_pk_add_f32 v[24:25], v[30:31], v[22:23]
	v_mul_f32_e32 v14, v21, v21
	v_mul_f32_e32 v8, v25, v25
	s_waitcnt lgkmcnt(0)
	v_pk_add_f32 v[22:23], v[18:19], v[28:29]
	v_pk_add_f32 v[26:27], v[16:17], v[26:27]
	v_fmac_f32_e32 v8, v24, v24
	v_fmac_f32_e32 v14, v20, v20
	v_add_f32_e32 v8, v8, v14
	v_mul_f32_e32 v14, v27, v27
	v_mul_f32_e32 v16, v23, v23
	v_fmac_f32_e32 v14, v26, v26
	v_fmac_f32_e32 v16, v22, v22
	v_add_f32_e32 v14, v14, v16
	v_add_f32_e32 v8, v8, v14
	v_cndmask_b32_e32 v14, v177, v32, vcc
	v_lshlrev_b32_e32 v37, 2, v14
	ds_bpermute_b32 v14, v37, v8
	v_cmp_lt_i32_e32 vcc, v34, v33
	s_add_i32 s39, s37, s2
	s_and_b32 s40, s39, 7
	s_ashr_i32 s16, s39, 3
	s_waitcnt lgkmcnt(0)
	v_add_f32_e32 v8, v8, v14
	v_cndmask_b32_e32 v14, v177, v34, vcc
	v_lshlrev_b32_e32 v38, 2, v14
	ds_bpermute_b32 v14, v38, v8
	s_lshl_b32 s0, s40, 12
	s_add_u32 s0, s30, s0
	s_addc_u32 s1, s31, 0
	v_lshlrev_b32_e32 v16, 3, v10
	s_and_saveexec_b64 s[24:25], s[6:7]
	s_cbranch_execz .LBB0_876
	v_mov_b32_e32 v17, v9
	v_lshl_add_u64 v[18:19], s[0:1], 0, v[16:17]
	s_ashr_i32 s17, s16, 31
	s_waitcnt lgkmcnt(0)
	v_add_f32_e32 v14, v8, v14
	v_lshl_add_u64 v[18:19], s[16:17], 3, v[18:19]
	global_store_dwordx2 v[18:19], v[14:15], off sc1

.LBB0_940:
	s_or_b64 exec, exec, s[0:1]
	v_lshl_or_b32 v30, s16, 5, v0
	v_lshl_or_b32 v28, s40, 4, v1
	v_readlane_b32 s40, v252, 14
	v_ashrrev_i32_e32 v31, 31, v30
	v_lshlrev_b32_e32 v44, 12, v28
	v_mov_b32_e32 v45, v9
	v_readlane_b32 s42, v252, 16
	v_readlane_b32 s43, v252, 17
	v_readlane_b32 s50, v252, 24
	v_readlane_b32 s51, v252, 25
	v_lshl_add_u64 v[44:45], s[42:43], 0, v[44:45]
	v_lshlrev_b64 v[46:47], 2, v[30:31]
	v_lshl_add_u64 v[56:57], v[44:45], 0, v[46:47]
	v_lshl_add_u64 v[52:53], s[50:51], 0, v[46:47]
	global_load_dwordx4 v[44:47], v[56:57], off
	global_load_dwordx4 v[48:51], v[52:53], off
	s_nop 0
	global_load_dwordx4 v[52:55], v[52:53], off offset:16
	s_nop 0
	global_load_dwordx4 v[56:59], v[56:57], off offset:16
	v_add_f32_e32 v14, 0, v14
	v_add_f32_e32 v14, v14, v17
	v_add_f32_e32 v14, v14, v19
	v_add_f32_e32 v14, v14, v39
	v_add_f32_e32 v14, v14, v40
	v_add_f32_e32 v14, v14, v41
	v_add_f32_e32 v14, v14, v42
	v_add_f32_e32 v14, v14, v43
	ds_bpermute_b32 v17, v37, v14
	v_readlane_b32 s41, v252, 15
	v_readlane_b32 s44, v252, 18
	v_readlane_b32 s45, v252, 19
	v_readlane_b32 s46, v252, 20
	s_waitcnt lgkmcnt(0)
	v_add_f32_e32 v14, v14, v17
	ds_bpermute_b32 v17, v38, v14
	v_readlane_b32 s47, v252, 21
	v_readlane_b32 s40, v252, 0
	v_readlane_b32 s44, v252, 4
	v_readlane_b32 s45, v252, 5
	s_waitcnt lgkmcnt(0)
	v_add_f32_e32 v14, v14, v17
	v_fmamk_f32 v14, v14, 0x3a800000, v35
	v_mul_f32_e32 v17, 0x4f800000, v14
	v_cmp_gt_f32_e32 vcc, s35, v14
	v_readlane_b32 s46, v252, 6
	v_readlane_b32 s47, v252, 7
	v_cndmask_b32_e32 v14, v14, v17, vcc
	v_sqrt_f32_e32 v17, v14
	s_mov_b64 s[24:25], s[44:45]
	v_mov_b32_e32 v41, v9
	v_lshlrev_b32_e32 v40, 11, v28
	v_add_u32_e32 v19, -1, v17
	v_add_u32_e32 v29, 1, v17
	v_fma_f32 v39, -v19, v17, v14
	v_fma_f32 v42, -v29, v17, v14
	v_cmp_ge_f32_e64 s[0:1], 0, v39
	s_mov_b64 s[26:27], s[46:47]
	v_lshl_add_u64 v[40:41], s[26:27], 0, v[40:41]
	v_cndmask_b32_e64 v17, v17, v19, s[0:1]
	v_cmp_lt_f32_e64 s[0:1], 0, v42
	v_lshl_add_u64 v[30:31], v[30:31], 1, v[40:41]
	v_readlane_b32 s48, v252, 22
	v_cndmask_b32_e64 v17, v17, v29, s[0:1]
	v_mul_f32_e32 v19, 0x37800000, v17
	v_cndmask_b32_e32 v17, v17, v19, vcc
	v_cmp_class_f32_e32 vcc, v14, v36
	v_readlane_b32 s49, v252, 23
	v_readlane_b32 s52, v252, 26
	v_cndmask_b32_e32 v14, v17, v14, vcc
	v_div_scale_f32 v17, s[0:1], v14, v14, 1.0
	v_rcp_f32_e32 v19, v17
	v_div_scale_f32 v29, vcc, 1.0, v14, 1.0
	s_lshl_b32 s0, s17, 3
	v_fma_f32 v39, -v17, v19, 1.0
	v_fmac_f32_e32 v19, v39, v19
	v_mul_f32_e32 v39, v29, v19
	v_fma_f32 v40, -v17, v39, v29
	v_fmac_f32_e32 v39, v40, v19
	v_fma_f32 v17, -v17, v39, v29
	v_div_fmas_f32 v17, v17, v19, v39
	v_div_fixup_f32 v14, v17, v14, 1.0
	v_pk_mul_f32 v[24:25], v[24:25], v[14:15] op_sel_hi:[1,0]
	v_pk_mul_f32 v[20:21], v[20:21], v[14:15] op_sel_hi:[1,0]
	v_pk_mul_f32 v[26:27], v[26:27], v[14:15] op_sel_hi:[1,0]
	v_pk_mul_f32 v[22:23], v[22:23], v[14:15] op_sel_hi:[1,0]
	s_add_u32 s0, s26, s0
	s_addc_u32 s1, s27, 0
	s_add_u32 s0, s0, 0xe4a8000
	s_addc_u32 s1, s1, 0
	v_readlane_b32 s53, v252, 27
	v_readlane_b32 s54, v252, 28
	v_readlane_b32 s55, v252, 29
	v_readlane_b32 s41, v252, 1
	v_readlane_b32 s42, v252, 2
	v_readlane_b32 s43, v252, 3
	s_waitcnt vmcnt(2)
	v_pk_fma_f32 v[40:41], v[50:51], v[20:21], v[46:47]
	v_pk_fma_f32 v[24:25], v[48:49], v[24:25], v[44:45]
	s_waitcnt vmcnt(0)
	v_pk_fma_f32 v[42:43], v[54:55], v[22:23], v[58:59]
	v_pk_fma_f32 v[26:27], v[52:53], v[26:27], v[56:57]
	v_cvt_pk_bf16_f32 v20, v24, v25
	v_mul_f32_e32 v14, v25, v25
	v_mul_f32_e32 v17, v41, v41
	v_mul_f32_e32 v19, v27, v27
	v_mul_f32_e32 v25, v43, v43
	v_fmac_f32_e32 v14, v24, v24
	v_fmac_f32_e32 v17, v40, v40
	v_fmac_f32_e32 v19, v26, v26
	v_fmac_f32_e32 v25, v42, v42
	v_add_f32_e32 v14, v14, v17
	v_add_f32_e32 v17, v19, v25
	v_add_f32_e32 v14, v14, v17
	ds_bpermute_b32 v17, v37, v14
	v_add_co_u32_e32 v24, vcc, s36, v30
	v_cvt_pk_bf16_f32 v21, v40, v41
	v_cvt_pk_bf16_f32 v22, v26, v27
	s_waitcnt lgkmcnt(0)
	v_add_f32_e32 v14, v14, v17
	ds_bpermute_b32 v17, v38, v14
	v_addc_co_u32_e32 v25, vcc, 0, v31, vcc
	v_cvt_pk_bf16_f32 v23, v42, v43
	global_store_dwordx4 v[24:25], v[20:23], off sc0 sc1
	s_and_saveexec_b64 s[24:25], s[6:7]
	s_cbranch_execz .LBB0_942
	s_waitcnt lgkmcnt(0)
	v_add_f32_e32 v14, v14, v17
	v_mov_b32_e32 v17, v9
	v_lshl_add_u64 v[16:17], s[0:1], 0, v[16:17]
	s_ashr_i32 s17, s16, 31
	v_lshl_add_u64 v[16:17], s[16:17], 3, v[16:17]
	global_store_dwordx2 v[16:17], v[14:15], off sc1

.LBB0_1006:
	s_or_b64 exec, exec, s[0:1]
	v_add_f32_e32 v8, 0, v8
	v_add_f32_e32 v8, v8, v14
	v_add_f32_e32 v8, v8, v20
	v_add_f32_e32 v8, v8, v21
	v_add_f32_e32 v8, v8, v22
	v_add_f32_e32 v8, v8, v23
	v_add_f32_e32 v8, v8, v24
	v_add_f32_e32 v8, v8, v26
	ds_bpermute_b32 v14, v37, v8
	s_cmp_lt_u32 s39, 8
	s_cselect_b64 s[0:1], -1, 0
	s_and_b64 s[0:1], s[6:7], s[0:1]
	s_waitcnt lgkmcnt(0)
	v_add_f32_e32 v8, v8, v14
	ds_bpermute_b32 v14, v38, v8
	s_and_saveexec_b64 s[16:17], s[0:1]
	s_cbranch_execz .LBB0_871
	s_waitcnt lgkmcnt(0)
	v_add_f32_e32 v8, v8, v14
	v_fmamk_f32 v8, v8, 0x3a800000, v35
	v_mul_f32_e32 v14, 0x4f800000, v8
	v_cmp_gt_f32_e32 vcc, s35, v8
	s_nop 1
	v_cndmask_b32_e32 v8, v8, v14, vcc
	v_sqrt_f32_e32 v14, v8
	s_nop 0
	v_add_u32_e32 v16, -1, v14
	v_fma_f32 v18, -v16, v14, v8
	v_add_u32_e32 v17, 1, v14
	v_cmp_ge_f32_e64 s[0:1], 0, v18
	s_nop 1
	v_cndmask_b32_e64 v16, v14, v16, s[0:1]
	v_fma_f32 v14, -v17, v14, v8
	v_cmp_lt_f32_e64 s[0:1], 0, v14
	s_nop 1
	v_cndmask_b32_e64 v14, v16, v17, s[0:1]
	v_mul_f32_e32 v16, 0x37800000, v14
	v_cndmask_b32_e32 v14, v14, v16, vcc
	v_cmp_class_f32_e32 vcc, v8, v36
	s_nop 1
	v_cndmask_b32_e32 v8, v14, v8, vcc
	v_div_scale_f32 v14, s[0:1], v8, v8, 1.0
	v_rcp_f32_e32 v16, v14
	s_nop 0
	v_fma_f32 v17, -v14, v16, 1.0
	v_fmac_f32_e32 v16, v17, v16
	v_div_scale_f32 v17, vcc, 1.0, v8, 1.0
	v_mul_f32_e32 v18, v17, v16
	v_fma_f32 v19, -v14, v18, v17
	v_fmac_f32_e32 v18, v19, v16
	v_fma_f32 v14, -v14, v18, v17
	v_div_fmas_f32 v14, v14, v16, v18
	v_div_fixup_f32 v8, v14, v8, 1.0
	v_lshlrev_b32_e32 v14, 2, v28
	global_store_dword v14, v8, s[10:11] sc0 sc1
	s_branch .LBB0_871
.LBB0_1008:
	s_waitcnt vmcnt(0)
	s_barrier
	s_mov_b64 s[0:1], exec
	v_readlane_b32 s2, v252, 9
	v_readlane_b32 s3, v252, 10
	s_and_b64 s[2:3], s[0:1], s[2:3]
	s_mov_b64 exec, s[2:3]
	s_cbranch_execz .LBB0_1060
	v_readlane_b32 s30, v252, 11
	v_readlane_b32 s31, v252, 12
	v_readlane_b32 s32, v252, 48
	v_mov_b32_e32 v5, 1
	v_mov_b32_e32 v22, 0
	s_add_u32 s36, s30, 0x10800
	s_addc_u32 s37, s31, 0
	s_and_b32 s32, s32, 63
	s_lshl_b32 s32, s32, 8
	s_add_u32 s34, s30, 0x8000
	s_addc_u32 s35, s31, 0
	v_mov_b32_e32 v4, s32
	global_atomic_add v22, v5, s[36:37]
	s_cmpk_lg_u32 s86, 0x100
	s_cbranch_scc1 .Lxb5_global
	s_cmp_eq_u32 s99, 0
	s_cbranch_scc1 .Lxb5_nowb
	buffer_wbl2 sc1
	s_waitcnt vmcnt(0)

.Lxb5_global:
	v_readlane_b32 s30, v252, 11
	v_readlane_b32 s31, v252, 12
	v_readlane_b32 s32, v252, 13
	v_mov_b32_e32 v5, 1
	v_mov_b32_e32 v22, 0
	s_add_u32 s34, s30, 0x1400
	s_addc_u32 s35, s31, 0
	s_lshl_b32 s32, s32, 8
	s_add_u32 s40, s30, 0x3400
	s_addc_u32 s41, s31, 0
	v_mov_b32_e32 v4, s32
	s_mov_b32 s42, 0
	global_atomic_add v6, v4, v5, s[34:35] sc0
	s_mul_i32 s33, s86, 5
	s_mul_i32 s39, s98, 5
	s_waitcnt vmcnt(0)
	v_readfirstlane_b32 s38, v6
	v_mov_b32_e32 v7, s98
	s_add_i32 s38, s38, 1
	s_cmp_lg_u32 s38, s39
	s_cbranch_scc1 .Lxb5_spin
	buffer_wbl2 sc1
	s_waitcnt vmcnt(0)
	global_atomic_add v22, v7, s[40:41]

.Lxb5_end:
.LBB0_1060:
	s_mov_b32 s100, 0
	s_or_b64 exec, exec, s[0:1]
	v_readlane_b32 s8, v252, 0
	v_readlane_b32 s9, v252, 1
	v_readlane_b32 s10, v252, 2
	v_readlane_b32 s11, v252, 3
	v_readlane_b32 s12, v252, 4
	v_readlane_b32 s13, v252, 5
	v_readlane_b32 s14, v252, 6
	v_readlane_b32 s15, v252, 7
	s_mov_b64 s[8:9], s[12:13]
	s_mov_b64 s[10:11], s[14:15]
	s_add_u32 s8, s10, 0x4160000
	s_addc_u32 s9, s11, 0
	v_mov_b32_e32 v9, v176
	s_waitcnt lgkmcnt(0)
	s_barrier
	s_cmpk_gt_i32 s72, 0x3ff
	v_readfirstlane_b32 s7, v9
	s_cbranch_scc1 .LBB0_1086
	s_ashr_i32 s2, s72, 31
	s_lshr_b32 s0, s2, 29
	s_add_i32 s3, s72, s0
	s_and_b32 s0, s3, -8
	s_sub_i32 s10, s72, s0
	s_cmp_gt_i32 s10, -1
	s_cbranch_scc0 .LBB0_1063
	s_lshl_b32 s6, s10, 7
	s_cbranch_execz .LBB0_1064
	s_branch .LBB0_1065

.LBB0_1082:
	s_cmp_lg_u32 s100, 0
	s_cbranch_scc1 .Lgd5_skip
	v_readlane_b32 s60, v252, 11
	v_readlane_b32 s61, v252, 12
	v_mov_b32_e32 v170, 0
	s_mov_b32 s62, 0
	s_add_u32 s60, s60, 0x10800
	s_addc_u32 s61, s61, 0
.Lgd5_spin:
	global_load_dword v171, v170, s[60:61] sc1
	s_waitcnt vmcnt(0)
	v_cmp_le_u32_e32 vcc, s86, v171
	s_cbranch_vccnz .Lgd5_ok
	s_add_i32 s62, s62, 1
	s_cmp_lt_u32 s62, 0x400000
	s_cbranch_scc0 .Lgd5_ok
	s_sleep 1
	s_branch .Lgd5_spin
.Lgd5_ok:
	s_mov_b32 s100, 1

.LBB0_1089:
	s_and_b32 s38, s29, 0xffffffe0
	s_ashr_i32 s39, s38, 31
	s_lshl_b64 s[38:39], s[38:39], 11
	s_add_u32 s38, s20, s38
	s_addc_u32 s39, s21, s39
	s_and_b32 s37, s24, 0x10000
	s_lshl_b32 s37, s37, 1
	s_add_u32 s40, s8, s37
	s_addc_u32 s41, s9, 0
	v_lshl_add_u64 v[96:97], s[38:39], 0, v[2:3]
	v_lshl_add_u64 v[68:69], s[40:41], 0, v[4:5]
	global_load_dwordx4 v[12:15], v[96:97], off sc1
	v_add_co_u32_e32 v16, vcc, s31, v68
	v_lshl_add_u64 v[98:99], s[38:39], 0, v[0:1]
	s_nop 0
	v_addc_co_u32_e32 v17, vcc, 0, v69, vcc
	v_add_co_u32_e32 v40, vcc, s33, v68
	global_load_dwordx4 v[16:19], v[16:17], off sc1
	s_nop 0
	v_addc_co_u32_e32 v41, vcc, 0, v69, vcc
	v_add_co_u32_e32 v52, vcc, s34, v68
	global_load_dwordx4 v[20:23], v[98:99], off sc1
	global_load_dwordx4 v[24:27], v[96:97], off offset:64 sc1
	global_load_dwordx4 v[28:31], v[98:99], off offset:64 sc1
	v_addc_co_u32_e32 v53, vcc, 0, v69, vcc
	v_add_co_u32_e32 v64, vcc, s35, v68
	v_lshl_add_u64 v[76:77], v[68:69], 0, s[6:7]
	v_lshl_add_u64 v[80:81], v[68:69], 0, s[10:11]
	v_lshl_add_u64 v[88:89], v[68:69], 0, s[12:13]
	v_addc_co_u32_e32 v65, vcc, 0, v69, vcc
	v_lshl_add_u64 v[100:101], v[68:69], 0, s[14:15]
	global_load_dwordx4 v[32:35], v[76:77], off offset:192 sc1
	global_load_dwordx4 v[44:47], v[80:81], off offset:192 sc1
	global_load_dwordx4 v[56:59], v[88:89], off offset:192 sc1
	global_load_dwordx4 v[68:71], v[100:101], off offset:192 sc1
	s_add_i32 s37, s2, s36
	global_load_dwordx4 v[40:43], v[40:41], off sc1
	s_cmpk_gt_i32 s37, 0x3ff
	global_load_dwordx4 v[52:55], v[52:53], off sc1
	s_cselect_b64 s[38:39], -1, 0
	global_load_dwordx4 v[64:67], v[64:65], off sc1
	s_nop 0
	global_load_dwordx4 v[72:75], v[76:77], off offset:64 sc1
	s_nop 0
	global_load_dwordx4 v[76:79], v[76:77], off offset:128 sc1
	s_or_b64 s[38:39], s[16:17], s[38:39]
	s_and_b64 vcc, exec, s[38:39]
	s_waitcnt vmcnt(12)
	v_mfma_f32_16x16x32_bf16 v[36:39], v[12:15], v[16:19], 0
	s_waitcnt vmcnt(11)
	v_mfma_f32_16x16x32_bf16 v[16:19], v[20:23], v[16:19], 0
	s_waitcnt vmcnt(1)
	v_mfma_f32_16x16x32_bf16 v[36:39], v[24:27], v[72:75], v[36:39]
	v_mfma_f32_16x16x32_bf16 v[16:19], v[28:31], v[72:75], v[16:19]
	global_load_dwordx4 v[72:75], v[80:81], off offset:64 sc1
	s_nop 0
	global_load_dwordx4 v[80:83], v[80:81], off offset:128 sc1
	s_nop 0
	global_load_dwordx4 v[84:87], v[88:89], off offset:64 sc1
	v_mfma_f32_16x16x32_bf16 v[48:51], v[12:15], v[40:43], 0
	v_mfma_f32_16x16x32_bf16 v[40:43], v[20:23], v[40:43], 0
	v_mfma_f32_16x16x32_bf16 v[60:63], v[12:15], v[52:55], 0
	v_mfma_f32_16x16x32_bf16 v[52:55], v[20:23], v[52:55], 0
	v_mfma_f32_16x16x32_bf16 v[12:15], v[12:15], v[64:67], 0
	v_mfma_f32_16x16x32_bf16 v[20:23], v[20:23], v[64:67], 0
	s_waitcnt vmcnt(2)
	v_mfma_f32_16x16x32_bf16 v[48:51], v[24:27], v[72:75], v[48:51]
	v_mfma_f32_16x16x32_bf16 v[40:43], v[28:31], v[72:75], v[40:43]
	global_load_dwordx4 v[72:75], v[96:97], off offset:128 sc1
	s_nop 0
	global_load_dwordx4 v[88:91], v[88:89], off offset:128 sc1
	s_nop 0
	global_load_dwordx4 v[92:95], v[98:99], off offset:128 sc1
	s_waitcnt vmcnt(3)
	v_mfma_f32_16x16x32_bf16 v[60:63], v[24:27], v[84:87], v[60:63]
	v_mfma_f32_16x16x32_bf16 v[52:55], v[28:31], v[84:87], v[52:55]
	global_load_dwordx4 v[84:87], v[96:97], off offset:192 sc1
	s_nop 0
	global_load_dwordx4 v[96:99], v[98:99], off offset:192 sc1
	s_waitcnt vmcnt(4)
	v_mfma_f32_16x16x32_bf16 v[36:39], v[72:75], v[76:79], v[36:39]
	s_waitcnt vmcnt(2)
	v_mfma_f32_16x16x32_bf16 v[16:19], v[92:95], v[76:79], v[16:19]
	v_mfma_f32_16x16x32_bf16 v[48:51], v[72:75], v[80:83], v[48:51]
	v_mfma_f32_16x16x32_bf16 v[52:55], v[92:95], v[88:91], v[52:55]
	v_mfma_f32_16x16x32_bf16 v[40:43], v[92:95], v[80:83], v[40:43]
	v_mfma_f32_16x16x32_bf16 v[60:63], v[72:75], v[88:91], v[60:63]
	s_waitcnt vmcnt(1)
	v_mfma_f32_16x16x32_bf16 v[36:39], v[84:87], v[32:35], v[36:39]
	s_waitcnt vmcnt(0)
	v_mfma_f32_16x16x32_bf16 v[16:19], v[96:99], v[32:35], v[16:19]
	v_mfma_f32_16x16x32_bf16 v[32:35], v[84:87], v[44:47], v[48:51]
	s_nop 4
	ds_write_b128 v11, v[36:39]
	v_mfma_f32_16x16x32_bf16 v[48:51], v[96:99], v[56:59], v[52:55]
	s_nop 2
	global_load_dwordx4 v[52:55], v[100:101], off offset:64 sc1
	v_mfma_f32_16x16x32_bf16 v[40:43], v[96:99], v[44:47], v[40:43]
	v_mfma_f32_16x16x32_bf16 v[44:47], v[84:87], v[56:59], v[60:63]
	global_load_dwordx4 v[56:59], v[100:101], off offset:128 sc1
	ds_write_b128 v11, v[16:19] offset:1024
	ds_write_b128 v11, v[32:35] offset:16384
	s_nop 3
	ds_write_b128 v11, v[40:43] offset:17408
	s_waitcnt vmcnt(1)
	v_mfma_f32_16x16x32_bf16 v[12:15], v[24:27], v[52:55], v[12:15]
	v_mfma_f32_16x16x32_bf16 v[20:23], v[28:31], v[52:55], v[20:23]
	s_waitcnt vmcnt(0)
	v_mfma_f32_16x16x32_bf16 v[12:15], v[72:75], v[56:59], v[12:15]
	v_mfma_f32_16x16x32_bf16 v[20:23], v[92:95], v[56:59], v[20:23]
	v_mfma_f32_16x16x32_bf16 v[12:15], v[84:87], v[68:71], v[12:15]
	ds_write_b128 v11, v[44:47] offset:32768
	ds_write_b128 v11, v[48:51] offset:33792
	s_nop 5
	ds_write_b128 v11, v[12:15] offset:49152
	v_mfma_f32_16x16x32_bf16 v[12:15], v[96:99], v[68:71], v[20:23]
	s_nop 7
	ds_write_b128 v11, v[12:15] offset:50176
	s_waitcnt lgkmcnt(0)
	s_barrier
	s_cbranch_vccnz .LBB0_1088
	s_and_b32 s37, s26, 0x70
	v_or_b32_e32 v6, s37, v8
	v_lshlrev_b32_e32 v12, 2, v6
	global_load_dword v76, v12, s[0:1] sc1
	v_add_u32_e32 v72, s22, v10
	ds_read_b128 v[12:15], v72
	ds_read_b128 v[16:19], v72 offset:1024
	ds_read_b128 v[20:23], v72 offset:2048
	ds_read_b128 v[24:27], v72 offset:3072
	ds_read_b128 v[28:31], v72 offset:4096
	ds_read_b128 v[32:35], v72 offset:5120
	ds_read_b128 v[36:39], v72 offset:6144
	ds_read_b128 v[40:43], v72 offset:7168
	ds_read_b128 v[44:47], v72 offset:8192
	ds_read_b128 v[48:51], v72 offset:9216
	ds_read_b128 v[52:55], v72 offset:10240
	ds_read_b128 v[56:59], v72 offset:11264
	ds_read_b128 v[60:63], v72 offset:12288
	ds_read_b128 v[64:67], v72 offset:13312
	ds_read_b128 v[68:71], v72 offset:14336
	ds_read_b128 v[72:75], v72 offset:15360
	s_waitcnt lgkmcnt(13)
	v_pk_add_f32 v[14:15], v[14:15], v[22:23]
	v_pk_add_f32 v[12:13], v[12:13], v[20:21]
	s_waitcnt lgkmcnt(12)
	v_pk_add_f32 v[16:17], v[16:17], v[24:25]
	v_pk_add_f32 v[18:19], v[18:19], v[26:27]
	s_waitcnt lgkmcnt(11)
	v_pk_add_f32 v[14:15], v[14:15], v[30:31]
	v_pk_add_f32 v[12:13], v[12:13], v[28:29]
	s_waitcnt lgkmcnt(10)
	v_pk_add_f32 v[16:17], v[16:17], v[32:33]
	v_pk_add_f32 v[18:19], v[18:19], v[34:35]
	s_waitcnt lgkmcnt(9)
	v_pk_add_f32 v[14:15], v[14:15], v[38:39]
	v_pk_add_f32 v[12:13], v[12:13], v[36:37]
	s_waitcnt lgkmcnt(8)
	v_pk_add_f32 v[16:17], v[16:17], v[40:41]
	s_add_i32 s37, s28, s29
	v_pk_add_f32 v[18:19], v[18:19], v[42:43]
	s_waitcnt lgkmcnt(7)
	v_pk_add_f32 v[14:15], v[14:15], v[46:47]
	v_pk_add_f32 v[12:13], v[12:13], v[44:45]
	s_waitcnt lgkmcnt(6)
	v_pk_add_f32 v[16:17], v[16:17], v[48:49]
	s_andn2_b32 s37, s37, 31
	v_readlane_b32 s40, v252, 0
	v_pk_add_f32 v[18:19], v[18:19], v[50:51]
	s_waitcnt lgkmcnt(5)
	v_pk_add_f32 v[14:15], v[14:15], v[54:55]
	v_pk_add_f32 v[12:13], v[12:13], v[52:53]
	s_waitcnt lgkmcnt(4)
	v_pk_add_f32 v[16:17], v[16:17], v[56:57]
	v_or_b32_e32 v78, s37, v9
	v_lshlrev_b32_e32 v6, 13, v6
	v_readlane_b32 s46, v252, 6
	v_readlane_b32 s47, v252, 7
	v_pk_add_f32 v[18:19], v[18:19], v[58:59]
	s_waitcnt lgkmcnt(3)
	v_pk_add_f32 v[14:15], v[14:15], v[62:63]
	v_pk_add_f32 v[12:13], v[12:13], v[60:61]
	s_waitcnt lgkmcnt(2)
	v_pk_add_f32 v[16:17], v[16:17], v[64:65]
	v_lshl_add_u64 v[80:81], s[46:47], 0, v[6:7]
	v_ashrrev_i32_e32 v79, 31, v78
	v_pk_add_f32 v[18:19], v[18:19], v[66:67]
	s_waitcnt lgkmcnt(1)
	v_pk_add_f32 v[14:15], v[14:15], v[70:71]
	v_pk_add_f32 v[12:13], v[12:13], v[68:69]
	s_waitcnt lgkmcnt(0)
	v_pk_add_f32 v[16:17], v[16:17], v[72:73]
	v_lshl_add_u64 v[78:79], v[78:79], 1, v[80:81]
	v_pk_add_f32 v[18:19], v[18:19], v[74:75]
	v_add_co_u32_e32 v78, vcc, 0xe1a0000, v78
	v_readlane_b32 s41, v252, 1
	s_nop 0
	v_addc_co_u32_e32 v79, vcc, 0, v79, vcc
	v_readlane_b32 s42, v252, 2
	v_readlane_b32 s43, v252, 3
	v_readlane_b32 s44, v252, 4
	v_readlane_b32 s45, v252, 5
	s_waitcnt vmcnt(0)
	v_pk_mul_f32 v[14:15], v[14:15], v[76:77] op_sel_hi:[1,0]
	v_pk_mul_f32 v[12:13], v[12:13], v[76:77] op_sel_hi:[1,0]
	v_pk_mul_f32 v[16:17], v[16:17], v[76:77] op_sel_hi:[1,0]
	v_pk_mul_f32 v[18:19], v[18:19], v[76:77] op_sel_hi:[1,0]
	v_max_f32_e32 v6, 0, v12
	v_max_f32_e32 v12, 0, v13
	v_max_f32_e32 v13, 0, v14
	v_max_f32_e32 v14, 0, v15
	v_max_f32_e32 v15, 0, v16
	v_max_f32_e32 v16, 0, v17
	v_max_f32_e32 v17, 0, v18
	v_max_f32_e32 v18, 0, v19
	v_mul_f32_e32 v12, v12, v12
	v_mul_f32_e32 v13, v13, v13
	v_mul_f32_e32 v14, v14, v14
	v_mul_f32_e32 v15, v15, v15
	v_mul_f32_e32 v6, v6, v6
	v_mul_f32_e32 v16, v16, v16
	v_mul_f32_e32 v17, v17, v17
	v_mul_f32_e32 v18, v18, v18
	v_cvt_pk_bf16_f32 v12, v6, v12
	v_cvt_pk_bf16_f32 v13, v13, v14
	v_cvt_pk_bf16_f32 v14, v15, v16
	v_cvt_pk_bf16_f32 v15, v17, v18
	global_store_dwordx4 v[78:79], v[12:15], off sc0 sc1
	s_branch .LBB0_1088
